# GEMM mainloop: LDS-DMA loads use SGPR base + 32-bit VGPR offset (no per-load 64-bit VALU address adds); LDS fragment base adds hoisted
# speedup vs baseline: 1.0291x; 1.0132x over previous
; DI f32x4 zero4() { float a, b, c, d; asm volatile("v_mov_b32 %0, 0\n\tv_mov_b32 %1, 0\n\tv_mov_b32 %2, 0\n\tv_mov_b32 %3, 0\n\ts_nop 1" : "=v"(a), "=v"(b), "=v"(c), "=v"(d)); return (f32x4){a, b, c, d}; }
; #define PG8_STAGE(bufoff, gbase, voff) do { _Pragma("unroll") for (int _i = 0; _i < 2; ++_i) \
;         __builtin_amdgcn_global_load_lds((const unsigned*)((const char*)(gbase) + (voff)[_i]), (LAS unsigned*)(lds + (bufoff) + ldsw + _i * 8192), 16, 0, 0); } while (0)
; #define PG8_WAIT_V(n) asm volatile("s_waitcnt vmcnt(" #n ")" ::: "memory")
; template <class Epi>
; DI void gemm_phase(LAS unsigned char* lds, const Gemm g, const StaticOrder& S, const Epi& E, const int tid) {
;     const int wid = __builtin_amdgcn_readfirstlane(tid >> 6), lane = tid & 63, wr = wid >> 2, wc = wid & 3, fr = lane & 15, fq = lane >> 4;
;     const int K = g.K, nt = K / BK;
;     unsigned voffA[2], voffB[2];
; #pragma unroll
;     for (int i = 0; i < 2; ++i) { int R, C; stage_rc(tid * 16 + i * 8192, R, C); const int Rb = Epi::PERM ? ((R & ~31) + perm32(R & 31)) : R;
;         voffA[i] = (unsigned)(R * K + C) * 2u; voffB[i] = (unsigned)(Rb * K + C) * 2u; }
;     const size_t kstep = (size_t)(BK * 2);
;     const size_t hstep = (size_t)HALF * K * 2;
;     const size_t tstep = 2 * hstep;
;     const unsigned ldsw = (unsigned)wid * 1024u;
;     const int aoff = lds_byte(wr * 64 + fr, fq * 8), boff = lds_byte(wc * 32 + fr, fq * 8);
;     ...
;     Unit cur, nxt; int ui = 0;
;     if (!S.next(0, cur)) return;
;     f32x4 acc[2][2][4][2];
; #pragma unroll
;     for (int a = 0; a < 2; ++a)
; #pragma unroll
;         for (int b = 0; b < 2; ++b)
; #pragma unroll
;             for (int m = 0; m < 4; ++m)
; #pragma unroll
;                 for (int n = 0; n < 2; ++n) acc[a][b][m][n] = zero4();
;     bf16x8 At[4][2], B0[2][2], B1[2][2];
;     const char* cA = (const char*)g.A + (size_t)cur.pm * tstep; const char* cB = (const char*)g.Bt + (size_t)cur.pn * tstep;
;     PG8_STAGE(PG8_SB(0, 0), cB, voffB); PG8_STAGE(PG8_SA(0, 0), cA, voffA); PG8_STAGE(PG8_SB(0, 1), cB + hstep, voffB); PG8_STAGE(PG8_SA(0, 1), cA + hstep, voffA);
;     if (wr == 1) PG8_BAR;
;     PG8_WAIT_V(4); PG8_BAR;
;     PG8_STAGE(PG8_SB(1, 0), cB + kstep, voffB); PG8_STAGE(PG8_SA(1, 0), cA + kstep, voffA); PG8_STAGE(PG8_SB(1, 1), cB + hstep + kstep, voffB);
;     PG8_WAIT_V(6); PG8_BAR;
.LBB0_734:
	v_lshl_add_u64 v[140:141], s[18:19], 0, v[198:199]
	v_mov_b32_e32 v129, v199
	v_lshl_add_u64 v[146:147], s[18:19], 0, v[128:129]
	v_mov_b32_e32 v133, v199
	s_add_i32 m0, s49, 0x18000
	v_lshl_add_u64 v[140:141], v[140:141], 0, s[46:47]
	v_lshl_add_u64 v[148:149], s[20:21], 0, v[132:133]
	v_mov_b32_e32 v131, v199
	s_waitcnt vmcnt(4)
	s_barrier
	global_load_lds_dwordx4 v[140:141], off
	v_lshl_add_u64 v[140:141], v[146:147], 0, s[46:47]
	s_add_i32 m0, s49, 0x1a000
	s_add_i32 s55, s49, 0x8000
	v_lshl_add_u64 v[150:151], s[20:21], 0, v[130:131]
	global_load_lds_dwordx4 v[140:141], off
	v_lshl_add_u64 v[140:141], v[148:149], 0, s[46:47]
	s_mov_b32 m0, s55
	s_add_i32 s56, s49, 0xa000
	v_lshl_add_u64 v[152:153], s[8:9], 0, v[198:199]
	global_load_lds_dwordx4 v[140:141], off
	v_lshl_add_u64 v[140:141], v[150:151], 0, s[46:47]
	s_mov_b32 m0, s56
	v_lshl_add_u64 v[154:155], s[8:9], 0, v[128:129]
	global_load_lds_dwordx4 v[140:141], off
	s_add_i32 m0, s49, 0x1c000
	v_lshl_add_u64 v[140:141], v[152:153], 0, s[46:47]
	global_load_lds_dwordx4 v[140:141], off
	v_lshl_add_u64 v[140:141], v[154:155], 0, s[46:47]
	s_add_i32 m0, s49, 0x1e000
	v_lshlrev_b32_e32 v146, 2, v142
	global_load_lds_dwordx4 v[140:141], off
	v_lshrrev_b32_e32 v140, 1, v143
	v_and_b32_e32 v140, 24, v140
	v_lshlrev_b32_e32 v141, 1, v140
	s_sext_i32_i16 s77, s6
	v_lshl_or_b32 v141, v142, 6, v141
	s_lshl_b32 s6, s11, 13
	v_and_b32_e32 v146, 32, v146
	v_bitop3_b32 v148, v141, s6, v146 bitop3:0xde
	s_lshl_b32 s6, s7, 5
	v_readlane_b32 s8, v255, 27
	s_and_b32 s6, s6, 0x60
	s_waitcnt vmcnt(6)
	v_add_u32_e32 v134, v139, v134
	v_add_u32_e32 v136, v138, v136
	v_readlane_b32 s9, v255, 28
	s_lshr_b32 s57, s91, 6
	s_lshl_b32 s7, s6, 7
	v_add_lshl_u32 v134, v134, v135, 1
	v_mov_b32_e32 v135, v199
	v_add_lshl_u32 v136, v136, v137, 1
	v_mov_b32_e32 v137, v199
	s_xor_b64 s[14:15], s[8:9], -1
	v_lshl_or_b32 v145, s11, 6, v142
	v_bitop3_b32 v146, s7, v141, v146 bitop3:0xf6
	s_add_i32 s60, s57, -2
	s_mov_b32 s11, s85
	v_or_b32_e32 v147, s6, v140
	v_lshl_add_u64 v[134:135], s[84:85], 0, v[134:135]
	v_lshl_add_u64 v[136:137], s[84:85], 0, v[136:137]
	s_mov_b32 s61, 0
	v_add_u32_e32 v148, 0, v148
	v_add_u32_e32 v212, 0x10000, v146
	v_add_u32_e32 v213, 0x14000, v146
	v_add_u32_e32 v214, 0x18000, v146
	v_add_u32_e32 v215, 0x1c000, v146
	s_barrier
	s_branch .LBB0_736

; #define PG8_STAGE(bufoff, gbase, voff) do { _Pragma("unroll") for (int _i = 0; _i < 2; ++_i) \
;         __builtin_amdgcn_global_load_lds((const unsigned*)((const char*)(gbase) + (voff)[_i]), (LAS unsigned*)(lds + (bufoff) + ldsw + _i * 8192), 16, 0, 0); } while (0)
; #define PG8_LDA(dst, b, h) do { _Pragma("unroll") for (int m = 0; m < 4; ++m) _Pragma("unroll") for (int k = 0; k < 2; ++k) dst[m][k] = *(const LAS bf16x8*)(lds + PG8_SA(b, h) + aoff + m * 2048 + k * 1024); } while (0)
; #define PG8_LDB(dst, b, h) do { _Pragma("unroll") for (int n = 0; n < 2; ++n) _Pragma("unroll") for (int k = 0; k < 2; ++k) dst[n][k] = *(const LAS bf16x8*)(lds + PG8_SB(b, h) + boff + n * 2048 + k * 1024); } while (0)
; #define PG8_MMA(ai, bj, At, Bt) do { __builtin_amdgcn_s_setprio(1); _Pragma("unroll") for (int m = 0; m < 4; ++m) _Pragma("unroll") for (int n = 0; n < 2; ++n) _Pragma("unroll") for (int k = 0; k < 2; ++k) \
;         acc[ai][bj][m][n] = __builtin_amdgcn_mfma_f32_16x16x32_bf16(Bt[n][k], At[m][k], acc[ai][bj][m][n], 0, 0, 0); __builtin_amdgcn_s_setprio(0); } while (0)
; #define PG8_WAIT_V(n) asm volatile("s_waitcnt vmcnt(" #n ")" ::: "memory")
; #define PG8_WAIT_L(n) asm volatile("s_waitcnt lgkmcnt(" #n ")" ::: "memory")
; #define PG8_BAR __builtin_amdgcn_s_barrier()
; template <class Epi>
; DI void gemm_phase(LAS unsigned char* lds, const Gemm g, const StaticOrder& S, const Epi& E, const int tid) {
;     ...
;         for (int t = 0; t < nt; t += 2) {
;             const bool last = (t == nt - 2);
;             const char* a1 = cA + (size_t)(t + 1) * kstep;
;             const char* a2 = last ? nA : cA + (size_t)(t + 2) * kstep; const char* b2 = last ? nB : cB + (size_t)(t + 2) * kstep;
;             const char* a3 = a2 + kstep; const char* b3 = b2 + kstep;
;             PG8_LDB(B0, 0, 0); PG8_SCHED; PG8_LDA(At, 0, 0); PG8_STAGE(PG8_SA(1, 1), a1 + hstep, voffA);
;             PG8_WAIT_L(8); PG8_BAR; PG8_WAIT_L(0); PG8_MMA(0, 0, At, B0); PG8_BAR; PG8_SCHED;
;             PG8_LDB(B1, 0, 1); PG8_STAGE(PG8_SB(0, 0), b2, voffB);
;             PG8_BAR; PG8_WAIT_L(0); PG8_MMA(0, 1, At, B1); PG8_BAR;
;             PG8_LDA(At, 0, 1); PG8_STAGE(PG8_SA(0, 0), a2, voffA);
;             PG8_BAR; PG8_WAIT_L(0); PG8_MMA(1, 0, At, B0); PG8_BAR; PG8_SCHED;
;             PG8_STAGE(PG8_SB(0, 1), b2 + hstep, voffB);
;             PG8_WAIT_V(6); PG8_BAR; PG8_MMA(1, 1, At, B1); PG8_BAR;
.LBB0_743:
	ds_read_b128 v[138:141], v212
	ds_read_b128 v[150:153], v212 offset:1024
	ds_read_b128 v[154:157], v212 offset:2048
	ds_read_b128 v[158:161], v212 offset:3072
	s_add_i32 s83, s18, 2
	s_add_u32 s22, s20, 0x80
	s_addc_u32 s19, s21, 0
	s_cmp_eq_u32 s60, s18
	s_cselect_b32 s18, s8, s22
	s_cselect_b32 s19, s9, s19
	s_cselect_b32 s23, s17, s82
	s_cselect_b32 s22, s16, s81
	s_add_i32 m0, s49, 0xc000
	ds_read_b128 v[162:165], v148
	ds_read_b128 v[166:169], v148 offset:1024
	ds_read_b128 v[170:173], v148 offset:2048
	ds_read_b128 v[174:177], v148 offset:3072
	ds_read_b128 v[178:181], v148 offset:4096
	ds_read_b128 v[182:185], v148 offset:5120
	ds_read_b128 v[186:189], v148 offset:6144
	ds_read_b128 v[190:193], v148 offset:7168
	global_load_lds_dwordx4 v134, s[20:21]
	s_add_i32 m0, s49, 0xe000
	s_nop 0
	global_load_lds_dwordx4 v136, s[20:21]
	s_waitcnt lgkmcnt(8)
	s_barrier
	s_waitcnt lgkmcnt(0)
	s_setprio 1
	s_waitcnt lgkmcnt(0)
	v_mfma_f32_16x16x32_bf16 v[24:27], v[138:141], v[162:165], v[24:27]
	v_mfma_f32_16x16x32_bf16 v[28:31], v[154:157], v[162:165], v[28:31]
	v_mfma_f32_16x16x32_bf16 v[16:19], v[138:141], v[170:173], v[16:19]
	v_mfma_f32_16x16x32_bf16 v[20:23], v[154:157], v[170:173], v[20:23]
	v_mfma_f32_16x16x32_bf16 v[8:11], v[138:141], v[178:181], v[8:11]
	v_mfma_f32_16x16x32_bf16 v[12:15], v[154:157], v[178:181], v[12:15]
	v_mfma_f32_16x16x32_bf16 v[0:3], v[138:141], v[186:189], v[0:3]
	v_mfma_f32_16x16x32_bf16 v[4:7], v[154:157], v[186:189], v[4:7]
	v_mfma_f32_16x16x32_bf16 v[24:27], v[150:153], v[166:169], v[24:27]
	v_mfma_f32_16x16x32_bf16 v[28:31], v[158:161], v[166:169], v[28:31]
	v_mfma_f32_16x16x32_bf16 v[16:19], v[150:153], v[174:177], v[16:19]
	v_mfma_f32_16x16x32_bf16 v[20:23], v[158:161], v[174:177], v[20:23]
	v_mfma_f32_16x16x32_bf16 v[8:11], v[150:153], v[182:185], v[8:11]
	v_mfma_f32_16x16x32_bf16 v[12:15], v[158:161], v[182:185], v[12:15]
	v_mfma_f32_16x16x32_bf16 v[0:3], v[150:153], v[190:193], v[0:3]
	v_mfma_f32_16x16x32_bf16 v[4:7], v[158:161], v[190:193], v[4:7]
	s_setprio 0
	s_barrier
	s_add_i32 s89, 0, 0x14000
	s_add_i32 vcc_lo, s26, s4
	s_mov_b32 m0, vcc_lo
	ds_read_b128 v[194:197], v213
	ds_read_b128 v[200:203], v213 offset:1024
	ds_read_b128 v[204:207], v213 offset:2048
	ds_read_b128 v[208:211], v213 offset:3072
	global_load_lds_dwordx4 v198, s[22:23]
	s_add_i32 m0, vcc_lo, 0x2000
	s_nop 0
	global_load_lds_dwordx4 v128, s[22:23]
	s_barrier
	s_waitcnt lgkmcnt(0)
	s_setprio 1
	s_waitcnt lgkmcnt(0)
	v_mfma_f32_16x16x32_bf16 v[88:91], v[194:197], v[162:165], v[88:91]
	v_mfma_f32_16x16x32_bf16 v[96:99], v[204:207], v[162:165], v[96:99]
	v_mfma_f32_16x16x32_bf16 v[80:83], v[194:197], v[170:173], v[80:83]
	v_mfma_f32_16x16x32_bf16 v[84:87], v[204:207], v[170:173], v[84:87]
	v_mfma_f32_16x16x32_bf16 v[72:75], v[194:197], v[178:181], v[72:75]
	v_mfma_f32_16x16x32_bf16 v[76:79], v[204:207], v[178:181], v[76:79]
	v_mfma_f32_16x16x32_bf16 v[56:59], v[194:197], v[186:189], v[56:59]
	v_mfma_f32_16x16x32_bf16 v[64:67], v[204:207], v[186:189], v[64:67]
	v_mfma_f32_16x16x32_bf16 v[88:91], v[200:203], v[166:169], v[88:91]
	v_mfma_f32_16x16x32_bf16 v[96:99], v[208:211], v[166:169], v[96:99]
	v_mfma_f32_16x16x32_bf16 v[80:83], v[200:203], v[174:177], v[80:83]
	v_mfma_f32_16x16x32_bf16 v[84:87], v[208:211], v[174:177], v[84:87]
	v_mfma_f32_16x16x32_bf16 v[72:75], v[200:203], v[182:185], v[72:75]
	v_mfma_f32_16x16x32_bf16 v[76:79], v[208:211], v[182:185], v[76:79]
	v_mfma_f32_16x16x32_bf16 v[56:59], v[200:203], v[190:193], v[56:59]
	v_mfma_f32_16x16x32_bf16 v[64:67], v[208:211], v[190:193], v[64:67]
	s_setprio 0
	s_mov_b32 m0, s49
	s_barrier
	ds_read_b128 v[162:165], v148 offset:16384
	ds_read_b128 v[166:169], v148 offset:17408
	ds_read_b128 v[170:173], v148 offset:18432
	ds_read_b128 v[174:177], v148 offset:19456
	ds_read_b128 v[178:181], v148 offset:20480
	ds_read_b128 v[182:185], v148 offset:21504
	ds_read_b128 v[186:189], v148 offset:22528
	ds_read_b128 v[190:193], v148 offset:23552
	global_load_lds_dwordx4 v132, s[18:19]
	s_mov_b32 m0, s52
	s_nop 0
	global_load_lds_dwordx4 v130, s[18:19]
	s_barrier
	s_waitcnt lgkmcnt(0)
	s_setprio 1
	s_waitcnt lgkmcnt(0)
	v_mfma_f32_16x16x32_bf16 v[60:63], v[138:141], v[162:165], v[60:63]
	v_mfma_f32_16x16x32_bf16 v[68:71], v[154:157], v[162:165], v[68:71]
	v_mfma_f32_16x16x32_bf16 v[48:51], v[138:141], v[170:173], v[48:51]
	v_mfma_f32_16x16x32_bf16 v[52:55], v[154:157], v[170:173], v[52:55]
	v_mfma_f32_16x16x32_bf16 v[40:43], v[138:141], v[178:181], v[40:43]
	v_mfma_f32_16x16x32_bf16 v[44:47], v[154:157], v[178:181], v[44:47]
	v_mfma_f32_16x16x32_bf16 v[32:35], v[138:141], v[186:189], v[32:35]
	v_mfma_f32_16x16x32_bf16 v[36:39], v[154:157], v[186:189], v[36:39]
	v_mfma_f32_16x16x32_bf16 v[60:63], v[150:153], v[166:169], v[60:63]
	v_mfma_f32_16x16x32_bf16 v[68:71], v[158:161], v[166:169], v[68:71]
	v_mfma_f32_16x16x32_bf16 v[48:51], v[150:153], v[174:177], v[48:51]
	v_mfma_f32_16x16x32_bf16 v[52:55], v[158:161], v[174:177], v[52:55]
	v_mfma_f32_16x16x32_bf16 v[40:43], v[150:153], v[182:185], v[40:43]
	v_mfma_f32_16x16x32_bf16 v[44:47], v[158:161], v[182:185], v[44:47]
	v_mfma_f32_16x16x32_bf16 v[32:35], v[150:153], v[190:193], v[32:35]
	v_mfma_f32_16x16x32_bf16 v[36:39], v[158:161], v[190:193], v[36:39]
	s_setprio 0
	s_barrier
	s_add_u32 s22, s22, s84
	s_addc_u32 s23, s23, 0
	s_add_i32 s89, s89, s4
	s_mov_b32 m0, s89
	s_nop 0
	global_load_lds_dwordx4 v198, s[22:23]
	s_add_i32 m0, s89, 0x2000
	s_nop 0
	global_load_lds_dwordx4 v128, s[22:23]
	s_waitcnt vmcnt(6)
	s_barrier
; #define PG8_STAGE(bufoff, gbase, voff) do { _Pragma("unroll") for (int _i = 0; _i < 2; ++_i) \
;         __builtin_amdgcn_global_load_lds((const unsigned*)((const char*)(gbase) + (voff)[_i]), (LAS unsigned*)(lds + (bufoff) + ldsw + _i * 8192), 16, 0, 0); } while (0)
; #define PG8_LDA(dst, b, h) do { _Pragma("unroll") for (int m = 0; m < 4; ++m) _Pragma("unroll") for (int k = 0; k < 2; ++k) dst[m][k] = *(const LAS bf16x8*)(lds + PG8_SA(b, h) + aoff + m * 2048 + k * 1024); } while (0)
; #define PG8_LDB(dst, b, h) do { _Pragma("unroll") for (int n = 0; n < 2; ++n) _Pragma("unroll") for (int k = 0; k < 2; ++k) dst[n][k] = *(const LAS bf16x8*)(lds + PG8_SB(b, h) + boff + n * 2048 + k * 1024); } while (0)
; #define PG8_MMA(ai, bj, At, Bt) do { __builtin_amdgcn_s_setprio(1); _Pragma("unroll") for (int m = 0; m < 4; ++m) _Pragma("unroll") for (int n = 0; n < 2; ++n) _Pragma("unroll") for (int k = 0; k < 2; ++k) \
;         acc[ai][bj][m][n] = __builtin_amdgcn_mfma_f32_16x16x32_bf16(Bt[n][k], At[m][k], acc[ai][bj][m][n], 0, 0, 0); __builtin_amdgcn_s_setprio(0); } while (0)
; #define PG8_WAIT_V(n) asm volatile("s_waitcnt vmcnt(" #n ")" ::: "memory")
; #define PG8_WAIT_L(n) asm volatile("s_waitcnt lgkmcnt(" #n ")" ::: "memory")
; #define PG8_BAR __builtin_amdgcn_s_barrier()
; #define PG8_SCHED __builtin_amdgcn_sched_barrier(0)
; template <class Epi>
; DI void gemm_phase(LAS unsigned char* lds, const Gemm g, const StaticOrder& S, const Epi& E, const int tid) {
;     ...
;             PG8_WAIT_V(6); PG8_BAR; PG8_MMA(1, 1, At, B1); PG8_BAR;
;             PG8_LDB(B0, 1, 0); PG8_SCHED; PG8_LDA(At, 1, 0); PG8_STAGE(PG8_SA(0, 1), a2 + hstep, voffA);
;             PG8_WAIT_L(8); PG8_BAR; PG8_WAIT_L(0); PG8_MMA(0, 0, At, B0); PG8_BAR; PG8_SCHED;
;             PG8_LDB(B1, 1, 1); PG8_STAGE(PG8_SB(1, 0), b3, voffB);
;             PG8_BAR; PG8_WAIT_L(0); PG8_MMA(0, 1, At, B1); PG8_BAR;
;             PG8_LDA(At, 1, 1); PG8_STAGE(PG8_SA(1, 0), a3, voffA);
	s_setprio 1
	v_mfma_f32_16x16x32_bf16 v[120:123], v[194:197], v[162:165], v[120:123]
	v_mfma_f32_16x16x32_bf16 v[124:127], v[204:207], v[162:165], v[124:127]
	v_mfma_f32_16x16x32_bf16 v[112:115], v[194:197], v[170:173], v[112:115]
	v_mfma_f32_16x16x32_bf16 v[116:119], v[204:207], v[170:173], v[116:119]
	v_mfma_f32_16x16x32_bf16 v[104:107], v[194:197], v[178:181], v[104:107]
	v_mfma_f32_16x16x32_bf16 v[108:111], v[204:207], v[178:181], v[108:111]
	v_mfma_f32_16x16x32_bf16 v[92:95], v[194:197], v[186:189], v[92:95]
	v_mfma_f32_16x16x32_bf16 v[100:103], v[204:207], v[186:189], v[100:103]
	v_mfma_f32_16x16x32_bf16 v[120:123], v[200:203], v[166:169], v[120:123]
	v_mfma_f32_16x16x32_bf16 v[124:127], v[208:211], v[166:169], v[124:127]
	v_mfma_f32_16x16x32_bf16 v[112:115], v[200:203], v[174:177], v[112:115]
	v_mfma_f32_16x16x32_bf16 v[116:119], v[208:211], v[174:177], v[116:119]
	v_mfma_f32_16x16x32_bf16 v[104:107], v[200:203], v[182:185], v[104:107]
	v_mfma_f32_16x16x32_bf16 v[108:111], v[208:211], v[182:185], v[108:111]
	v_mfma_f32_16x16x32_bf16 v[92:95], v[200:203], v[190:193], v[92:95]
	v_mfma_f32_16x16x32_bf16 v[100:103], v[208:211], v[190:193], v[100:103]
	s_setprio 0
	s_add_i32 s22, 0, 0x18000
	s_barrier
	ds_read_b128 v[138:141], v214
	ds_read_b128 v[150:153], v214 offset:1024
	ds_read_b128 v[154:157], v214 offset:2048
	ds_read_b128 v[158:161], v214 offset:3072
	s_add_u32 s18, s18, s84
	s_addc_u32 s19, s19, 0
	s_mov_b32 m0, s53
	ds_read_b128 v[162:165], v148 offset:32768
	ds_read_b128 v[166:169], v148 offset:33792
	ds_read_b128 v[170:173], v148 offset:34816
	ds_read_b128 v[174:177], v148 offset:35840
	ds_read_b128 v[178:181], v148 offset:36864
	ds_read_b128 v[182:185], v148 offset:37888
	ds_read_b128 v[186:189], v148 offset:38912
	ds_read_b128 v[190:193], v148 offset:39936
	global_load_lds_dwordx4 v132, s[18:19]
	s_mov_b32 m0, s54
	s_nop 0
	global_load_lds_dwordx4 v130, s[18:19]
	s_waitcnt lgkmcnt(8)
	s_barrier
	s_waitcnt lgkmcnt(0)
	s_setprio 1
	s_waitcnt lgkmcnt(0)
	v_mfma_f32_16x16x32_bf16 v[24:27], v[138:141], v[162:165], v[24:27]
	v_mfma_f32_16x16x32_bf16 v[28:31], v[154:157], v[162:165], v[28:31]
	v_mfma_f32_16x16x32_bf16 v[16:19], v[138:141], v[170:173], v[16:19]
	v_mfma_f32_16x16x32_bf16 v[20:23], v[154:157], v[170:173], v[20:23]
	v_mfma_f32_16x16x32_bf16 v[8:11], v[138:141], v[178:181], v[8:11]
	v_mfma_f32_16x16x32_bf16 v[12:15], v[154:157], v[178:181], v[12:15]
	v_mfma_f32_16x16x32_bf16 v[0:3], v[138:141], v[186:189], v[0:3]
	v_mfma_f32_16x16x32_bf16 v[4:7], v[154:157], v[186:189], v[4:7]
	v_mfma_f32_16x16x32_bf16 v[24:27], v[150:153], v[166:169], v[24:27]
	v_mfma_f32_16x16x32_bf16 v[28:31], v[158:161], v[166:169], v[28:31]
	v_mfma_f32_16x16x32_bf16 v[16:19], v[150:153], v[174:177], v[16:19]
	v_mfma_f32_16x16x32_bf16 v[20:23], v[158:161], v[174:177], v[20:23]
	v_mfma_f32_16x16x32_bf16 v[8:11], v[150:153], v[182:185], v[8:11]
	v_mfma_f32_16x16x32_bf16 v[12:15], v[158:161], v[182:185], v[12:15]
	v_mfma_f32_16x16x32_bf16 v[0:3], v[150:153], v[190:193], v[0:3]
	v_mfma_f32_16x16x32_bf16 v[4:7], v[158:161], v[190:193], v[4:7]
	s_setprio 0
	s_barrier
	s_add_i32 s18, 0, 0x1c000
	s_add_i32 s19, s22, s4
	s_mov_b32 m0, s19
	ds_read_b128 v[194:197], v215
	ds_read_b128 v[200:203], v215 offset:1024
	ds_read_b128 v[204:207], v215 offset:2048
	ds_read_b128 v[208:211], v215 offset:3072
	s_add_i32 vcc_hi, s60, 2
	s_cmp_eq_u32 vcc_hi, s83
	s_cselect_b32 s100, s16, s81
	s_cselect_b32 s101, s17, s82
	s_add_u32 s100, s100, 0x80
	s_addc_u32 s101, s101, 0
	global_load_lds_dwordx4 v198, s[100:101]
	s_add_i32 m0, s19, 0x2000
	s_nop 0
	global_load_lds_dwordx4 v128, s[100:101]
	s_barrier
	s_waitcnt lgkmcnt(0)
	s_setprio 1
	s_waitcnt lgkmcnt(0)
	v_mfma_f32_16x16x32_bf16 v[88:91], v[194:197], v[162:165], v[88:91]
	v_mfma_f32_16x16x32_bf16 v[96:99], v[204:207], v[162:165], v[96:99]
	v_mfma_f32_16x16x32_bf16 v[80:83], v[194:197], v[170:173], v[80:83]
	v_mfma_f32_16x16x32_bf16 v[84:87], v[204:207], v[170:173], v[84:87]
	v_mfma_f32_16x16x32_bf16 v[72:75], v[194:197], v[178:181], v[72:75]
	v_mfma_f32_16x16x32_bf16 v[76:79], v[204:207], v[178:181], v[76:79]
	v_mfma_f32_16x16x32_bf16 v[56:59], v[194:197], v[186:189], v[56:59]
	v_mfma_f32_16x16x32_bf16 v[64:67], v[204:207], v[186:189], v[64:67]
	v_mfma_f32_16x16x32_bf16 v[88:91], v[200:203], v[166:169], v[88:91]
	v_mfma_f32_16x16x32_bf16 v[96:99], v[208:211], v[166:169], v[96:99]
	v_mfma_f32_16x16x32_bf16 v[80:83], v[200:203], v[174:177], v[80:83]
	v_mfma_f32_16x16x32_bf16 v[84:87], v[208:211], v[174:177], v[84:87]
	v_mfma_f32_16x16x32_bf16 v[72:75], v[200:203], v[182:185], v[72:75]
	v_mfma_f32_16x16x32_bf16 v[76:79], v[208:211], v[182:185], v[76:79]
	v_mfma_f32_16x16x32_bf16 v[56:59], v[200:203], v[190:193], v[56:59]
	v_mfma_f32_16x16x32_bf16 v[64:67], v[208:211], v[190:193], v[64:67]
	s_setprio 0
	s_mov_b32 m0, s55
	s_barrier
	ds_read_b128 v[162:165], v148 offset:49152
	ds_read_b128 v[166:169], v148 offset:50176
	ds_read_b128 v[170:173], v148 offset:51200
	ds_read_b128 v[174:177], v148 offset:52224
	ds_read_b128 v[178:181], v148 offset:53248
	ds_read_b128 v[182:185], v148 offset:54272
	ds_read_b128 v[186:189], v148 offset:55296
	ds_read_b128 v[190:193], v148 offset:56320
	s_add_u32 s100, s20, 0x80
	s_addc_u32 s101, s21, 0
	s_add_i32 vcc_hi, s60, 2
	s_cmp_eq_u32 vcc_hi, s83
	s_cselect_b32 s100, s8, s100
	s_cselect_b32 s101, s9, s101
	s_add_u32 s100, s100, 0x80
	s_addc_u32 s101, s101, 0
	global_load_lds_dwordx4 v132, s[100:101]
	s_mov_b32 m0, s56
	s_nop 0
	global_load_lds_dwordx4 v130, s[100:101]
	s_barrier
; DI unsigned pk2(float lo, float hi) { f32x2 v = {lo, hi}; bf16v2 b = __builtin_convertvector(v, bf16v2); return __builtin_bit_cast(unsigned, b); }
; DI float silu_f(float x) { return x * __builtin_amdgcn_rcpf(1.f + __expf(-x)); }
; #define PG8_STAGE(bufoff, gbase, voff) do { _Pragma("unroll") for (int _i = 0; _i < 2; ++_i) \
;         __builtin_amdgcn_global_load_lds((const unsigned*)((const char*)(gbase) + (voff)[_i]), (LAS unsigned*)(lds + (bufoff) + ldsw + _i * 8192), 16, 0, 0); } while (0)
; #define PG8_LDA(dst, b, h) do { _Pragma("unroll") for (int m = 0; m < 4; ++m) _Pragma("unroll") for (int k = 0; k < 2; ++k) dst[m][k] = *(const LAS bf16x8*)(lds + PG8_SA(b, h) + aoff + m * 2048 + k * 1024); } while (0)
; #define PG8_MMA(ai, bj, At, Bt) do { __builtin_amdgcn_s_setprio(1); _Pragma("unroll") for (int m = 0; m < 4; ++m) _Pragma("unroll") for (int n = 0; n < 2; ++n) _Pragma("unroll") for (int k = 0; k < 2; ++k) \
;         acc[ai][bj][m][n] = __builtin_amdgcn_mfma_f32_16x16x32_bf16(Bt[n][k], At[m][k], acc[ai][bj][m][n], 0, 0, 0); __builtin_amdgcn_s_setprio(0); } while (0)
;     DI void operator()(const f32x4 (&acc)[2][2][4][2], const Unit& u, int wr, int wc, int fr, int fq) const {
;         const int row0 = u.pm * BM + wr * 64 + fr, col0 = u.pn * HALF + wc * 32 + 8 * fq;
; #pragma unroll
;         for (int ai = 0; ai < 2; ++ai)
; #pragma unroll
;             for (int m = 0; m < 4; ++m) { bf16_t* rowp = O + (size_t)(row0 + ai * HALF + m * 16) * ldc + col0;
;                 float r[8];
; #pragma unroll
;                 for (int n = 0; n < 2; ++n)
; #pragma unroll
;                     for (int e = 0; e < 4; ++e) { const float g = acc[ai][0][m][n][e], up = acc[ai][1][m][n][e]; r[n * 4 + e] = silu_f(g) * up; }
;                 u32x4 o; o.x = pk2(r[0], r[1]); o.y = pk2(r[2], r[3]); o.z = pk2(r[4], r[5]); o.w = pk2(r[6], r[7]);
;                 *(u32x4*)rowp = o; }
; template <class Epi>
; DI void gemm_phase(LAS unsigned char* lds, const Gemm g, const StaticOrder& S, const Epi& E, const int tid) {
;     ...
;             PG8_LDA(At, 1, 1); PG8_STAGE(PG8_SA(1, 0), a3, voffA);
;             PG8_BAR; PG8_WAIT_L(0); PG8_MMA(1, 0, At, B0); PG8_BAR; PG8_SCHED;
;             PG8_STAGE(PG8_SB(1, 1), b3 + hstep, voffB);
;             PG8_WAIT_V(6); PG8_BAR; PG8_MMA(1, 1, At, B1); PG8_BAR;
;         }
;         E(acc, cur, wr, wc, fr, fq);
	s_waitcnt lgkmcnt(0)
	s_setprio 1
	s_waitcnt lgkmcnt(0)
	v_mfma_f32_16x16x32_bf16 v[60:63], v[138:141], v[162:165], v[60:63]
	v_mfma_f32_16x16x32_bf16 v[68:71], v[154:157], v[162:165], v[68:71]
	v_mfma_f32_16x16x32_bf16 v[48:51], v[138:141], v[170:173], v[48:51]
	v_mfma_f32_16x16x32_bf16 v[52:55], v[154:157], v[170:173], v[52:55]
	v_mfma_f32_16x16x32_bf16 v[40:43], v[138:141], v[178:181], v[40:43]
	v_mfma_f32_16x16x32_bf16 v[44:47], v[154:157], v[178:181], v[44:47]
	v_mfma_f32_16x16x32_bf16 v[32:35], v[138:141], v[186:189], v[32:35]
	v_mfma_f32_16x16x32_bf16 v[36:39], v[154:157], v[186:189], v[36:39]
	v_mfma_f32_16x16x32_bf16 v[60:63], v[150:153], v[166:169], v[60:63]
	v_mfma_f32_16x16x32_bf16 v[68:71], v[158:161], v[166:169], v[68:71]
	v_mfma_f32_16x16x32_bf16 v[48:51], v[150:153], v[174:177], v[48:51]
	v_mfma_f32_16x16x32_bf16 v[52:55], v[158:161], v[174:177], v[52:55]
	v_mfma_f32_16x16x32_bf16 v[40:43], v[150:153], v[182:185], v[40:43]
	v_mfma_f32_16x16x32_bf16 v[44:47], v[158:161], v[182:185], v[44:47]
	v_mfma_f32_16x16x32_bf16 v[32:35], v[150:153], v[190:193], v[32:35]
	v_mfma_f32_16x16x32_bf16 v[36:39], v[158:161], v[190:193], v[36:39]
	s_setprio 0
	s_barrier
	s_add_i32 s18, s18, s4
	s_add_i32 vcc_hi, s60, 2
	s_cmp_eq_u32 vcc_hi, s83
	s_cselect_b32 s100, s16, s81
	s_cselect_b32 s101, s17, s82
	s_add_u32 s100, s100, s84
	s_addc_u32 s101, s101, 0
	s_add_u32 s100, s100, 0x80
	s_addc_u32 s101, s101, 0
	s_mov_b32 m0, s18
	s_nop 0
	global_load_lds_dwordx4 v198, s[100:101]
	s_add_i32 m0, s18, 0x2000
	s_nop 0
	global_load_lds_dwordx4 v128, s[100:101]
	s_waitcnt vmcnt(6)
	s_barrier
	s_setprio 1
	v_mfma_f32_16x16x32_bf16 v[120:123], v[194:197], v[162:165], v[120:123]
	v_mfma_f32_16x16x32_bf16 v[124:127], v[204:207], v[162:165], v[124:127]
	v_mfma_f32_16x16x32_bf16 v[112:115], v[194:197], v[170:173], v[112:115]
	v_mfma_f32_16x16x32_bf16 v[116:119], v[204:207], v[170:173], v[116:119]
	v_mfma_f32_16x16x32_bf16 v[104:107], v[194:197], v[178:181], v[104:107]
	v_mfma_f32_16x16x32_bf16 v[108:111], v[204:207], v[178:181], v[108:111]
	v_mfma_f32_16x16x32_bf16 v[92:95], v[194:197], v[186:189], v[92:95]
	v_mfma_f32_16x16x32_bf16 v[100:103], v[204:207], v[186:189], v[100:103]
	v_mfma_f32_16x16x32_bf16 v[120:123], v[200:203], v[166:169], v[120:123]
	v_mfma_f32_16x16x32_bf16 v[124:127], v[208:211], v[166:169], v[124:127]
	v_mfma_f32_16x16x32_bf16 v[112:115], v[200:203], v[174:177], v[112:115]
	v_mfma_f32_16x16x32_bf16 v[116:119], v[208:211], v[174:177], v[116:119]
	v_mfma_f32_16x16x32_bf16 v[104:107], v[200:203], v[182:185], v[104:107]
	v_mfma_f32_16x16x32_bf16 v[108:111], v[208:211], v[182:185], v[108:111]
	v_mfma_f32_16x16x32_bf16 v[92:95], v[200:203], v[190:193], v[92:95]
	v_mfma_f32_16x16x32_bf16 v[100:103], v[208:211], v[190:193], v[100:103]
	s_setprio 0
	s_add_u32 s20, s20, 0x100
	s_addc_u32 s21, s21, 0
	s_add_u32 s81, s81, 0x100
	s_addc_u32 s82, s82, 0
	s_cmp_ge_u32 s83, s57
	s_mov_b32 s18, s83
	s_barrier
	s_cbranch_scc0 .LBB0_743
	v_lshl_add_u32 v140, s80, 8, v145
	v_ashrrev_i32_e32 v138, 31, v140
	v_mul_lo_u32 v157, s78, v138
	v_mul_lo_u32 v141, s79, v140
	v_mad_u64_u32 v[138:139], s[18:19], s78, v140, 0
	v_or_b32_e32 v162, 16, v140
	v_or_b32_e32 v160, 32, v140
	v_or_b32_e32 v158, 48, v140
	v_add_u32_e32 v154, 0x80, v140
	v_add_u32_e32 v151, 0x90, v140
	v_add3_u32 v139, v139, v157, v141
	s_mov_b64 s[18:19], -1
	s_andn2_b64 vcc, exec, s[14:15]
	v_mul_lo_u32 v163, s79, v162
	v_mul_lo_u32 v161, s79, v160
	v_mul_lo_u32 v159, s79, v158
	v_ashrrev_i32_e32 v156, 31, v154
	v_mul_lo_u32 v155, s79, v154
	v_ashrrev_i32_e32 v153, 31, v151
	v_mul_lo_u32 v152, s79, v151
	v_add_u32_e32 v150, 0xa0, v140
	v_add_u32_e32 v149, 0xb0, v140
	s_cbranch_vccnz .LBB0_746
	v_mul_f32_e32 v140, 0xbfb8aa3b, v24
	v_mul_f32_e32 v141, 0xbfb8aa3b, v25
	v_mul_f32_e32 v166, 0xbfb8aa3b, v26
	v_mul_f32_e32 v167, 0xbfb8aa3b, v27
	v_mul_f32_e32 v168, 0xbfb8aa3b, v28
	v_mul_f32_e32 v169, 0xbfb8aa3b, v29
	v_exp_f32_e32 v140, v140
	v_exp_f32_e32 v141, v141
	v_exp_f32_e32 v166, v166
	v_exp_f32_e32 v167, v167
	v_exp_f32_e32 v168, v168
	v_exp_f32_e32 v169, v169
	v_mul_f32_e32 v170, 0xbfb8aa3b, v30
	v_mul_f32_e32 v171, 0xbfb8aa3b, v31
	v_add_f32_e32 v140, 1.0, v140
	v_add_f32_e32 v141, 1.0, v141
	v_add_f32_e32 v166, 1.0, v166
	v_add_f32_e32 v167, 1.0, v167
	v_add_f32_e32 v168, 1.0, v168
	v_add_f32_e32 v169, 1.0, v169
	v_exp_f32_e32 v170, v170
	v_exp_f32_e32 v171, v171
	v_rcp_f32_e32 v164, v140
	v_rcp_f32_e32 v165, v141
	v_rcp_f32_e32 v166, v166
	v_rcp_f32_e32 v167, v167
	v_rcp_f32_e32 v168, v168
	v_rcp_f32_e32 v169, v169
	v_add_f32_e32 v170, 1.0, v170
	v_add_f32_e32 v171, 1.0, v171
	v_pk_mul_f32 v[164:165], v[24:25], v[164:165]
	v_pk_mul_f32 v[166:167], v[26:27], v[166:167]
	v_rcp_f32_e32 v170, v170
	v_rcp_f32_e32 v171, v171
	v_pk_mul_f32 v[168:169], v[28:29], v[168:169]
	v_pk_mul_f32 v[164:165], v[164:165], v[88:89]
	v_pk_mul_f32 v[166:167], v[166:167], v[90:91]
	v_pk_mul_f32 v[168:169], v[168:169], v[96:97]
	v_cvt_pk_bf16_f32 v164, v164, v165
	v_cvt_pk_bf16_f32 v165, v166, v167
	v_cvt_pk_bf16_f32 v166, v168, v169
	v_mul_f32_e32 v168, 0xbfb8aa3b, v16
	v_mul_f32_e32 v169, 0xbfb8aa3b, v17
	v_lshl_or_b32 v140, s77, 7, v147
	v_readlane_b32 s18, v255, 30
	v_exp_f32_e32 v168, v168
	v_exp_f32_e32 v169, v169
	v_ashrrev_i32_e32 v141, 31, v140
	v_readlane_b32 s19, v255, 31
	v_pk_mul_f32 v[170:171], v[30:31], v[170:171]
	s_nop 0
	v_lshl_add_u64 v[140:141], v[140:141], 1, s[18:19]
	v_pk_mul_f32 v[170:171], v[170:171], v[98:99]
	v_lshl_add_u64 v[172:173], v[138:139], 1, v[140:141]
	v_cvt_pk_bf16_f32 v167, v170, v171
	global_store_dwordx4 v[172:173], v[164:167], off
	v_mul_f32_e32 v170, 0xbfb8aa3b, v20
; DI unsigned pk2(float lo, float hi) { f32x2 v = {lo, hi}; bf16v2 b = __builtin_convertvector(v, bf16v2); return __builtin_bit_cast(unsigned, b); }
; DI float silu_f(float x) { return x * __builtin_amdgcn_rcpf(1.f + __expf(-x)); }
;     DI void operator()(const f32x4 (&acc)[2][2][4][2], const Unit& u, int wr, int wc, int fr, int fq) const {
;         const int row0 = u.pm * BM + wr * 64 + fr, col0 = u.pn * HALF + wc * 32 + 8 * fq;
; #pragma unroll
;         for (int ai = 0; ai < 2; ++ai)
; #pragma unroll
;             for (int m = 0; m < 4; ++m) { bf16_t* rowp = O + (size_t)(row0 + ai * HALF + m * 16) * ldc + col0;
;                 float r[8];
; #pragma unroll
;                 for (int n = 0; n < 2; ++n)
; #pragma unroll
;                     for (int e = 0; e < 4; ++e) { const float g = acc[ai][0][m][n][e], up = acc[ai][1][m][n][e]; r[n * 4 + e] = silu_f(g) * up; }
;                 u32x4 o; o.x = pk2(r[0], r[1]); o.y = pk2(r[2], r[3]); o.z = pk2(r[4], r[5]); o.w = pk2(r[6], r[7]);
;                 *(u32x4*)rowp = o; }
	v_mul_f32_e32 v171, 0xbfb8aa3b, v21
	v_add_f32_e32 v164, 1.0, v168
	v_add_f32_e32 v165, 1.0, v169
	v_mul_f32_e32 v168, 0xbfb8aa3b, v18
	v_mul_f32_e32 v169, 0xbfb8aa3b, v19
	v_exp_f32_e32 v168, v168
	v_exp_f32_e32 v169, v169
	v_mul_f32_e32 v172, 0xbfb8aa3b, v22
	v_mul_f32_e32 v173, 0xbfb8aa3b, v23
	v_add_f32_e32 v168, 1.0, v168
	v_add_f32_e32 v169, 1.0, v169
	v_exp_f32_e32 v170, v170
	v_exp_f32_e32 v171, v171
	v_exp_f32_e32 v172, v172
	v_exp_f32_e32 v173, v173
	v_rcp_f32_e32 v164, v164
	v_rcp_f32_e32 v165, v165
	v_rcp_f32_e32 v168, v168
	v_rcp_f32_e32 v169, v169
	v_add_f32_e32 v170, 1.0, v170
	v_add_f32_e32 v171, 1.0, v171
	v_add_f32_e32 v172, 1.0, v172
	v_add_f32_e32 v173, 1.0, v173
	v_pk_mul_f32 v[164:165], v[16:17], v[164:165]
	v_pk_mul_f32 v[168:169], v[18:19], v[168:169]
	v_rcp_f32_e32 v170, v170
	v_rcp_f32_e32 v171, v171
	v_rcp_f32_e32 v172, v172
	v_rcp_f32_e32 v173, v173
	v_pk_mul_f32 v[164:165], v[164:165], v[80:81]
	v_pk_mul_f32 v[168:169], v[168:169], v[82:83]
	v_cvt_pk_bf16_f32 v164, v164, v165
	v_cvt_pk_bf16_f32 v165, v168, v169
	v_mul_f32_e32 v168, 0xbfb8aa3b, v8
	v_mul_f32_e32 v169, 0xbfb8aa3b, v9
	v_exp_f32_e32 v168, v168
	v_exp_f32_e32 v169, v169
	v_mad_u64_u32 v[166:167], s[18:19], s78, v162, 0
	v_pk_mul_f32 v[170:171], v[20:21], v[170:171]
	v_pk_mul_f32 v[172:173], v[22:23], v[172:173]
	v_add3_u32 v167, v167, v157, v163
	v_pk_mul_f32 v[170:171], v[170:171], v[84:85]
	v_pk_mul_f32 v[172:173], v[172:173], v[86:87]
	v_lshl_add_u64 v[174:175], v[166:167], 1, v[140:141]
	v_cvt_pk_bf16_f32 v166, v170, v171
	v_cvt_pk_bf16_f32 v167, v172, v173
	global_store_dwordx4 v[174:175], v[164:167], off
	v_mul_f32_e32 v170, 0xbfb8aa3b, v12
	v_mul_f32_e32 v171, 0xbfb8aa3b, v13
	v_add_f32_e32 v164, 1.0, v168
	v_add_f32_e32 v165, 1.0, v169
	v_mul_f32_e32 v168, 0xbfb8aa3b, v10
	v_mul_f32_e32 v169, 0xbfb8aa3b, v11
	v_exp_f32_e32 v168, v168
	v_exp_f32_e32 v169, v169
	v_mul_f32_e32 v172, 0xbfb8aa3b, v14
	v_mul_f32_e32 v173, 0xbfb8aa3b, v15
	v_add_f32_e32 v168, 1.0, v168
	v_add_f32_e32 v169, 1.0, v169
	v_exp_f32_e32 v170, v170
	v_exp_f32_e32 v171, v171
	v_exp_f32_e32 v172, v172
	v_exp_f32_e32 v173, v173
	v_rcp_f32_e32 v164, v164
	v_rcp_f32_e32 v165, v165
	v_rcp_f32_e32 v168, v168
	v_rcp_f32_e32 v169, v169
	v_add_f32_e32 v170, 1.0, v170
	v_add_f32_e32 v171, 1.0, v171
	v_add_f32_e32 v172, 1.0, v172
	v_add_f32_e32 v173, 1.0, v173
	v_pk_mul_f32 v[164:165], v[8:9], v[164:165]
	v_pk_mul_f32 v[168:169], v[10:11], v[168:169]
	v_rcp_f32_e32 v170, v170
	v_rcp_f32_e32 v171, v171
	v_rcp_f32_e32 v172, v172
	v_rcp_f32_e32 v173, v173
	v_pk_mul_f32 v[164:165], v[164:165], v[72:73]
	v_pk_mul_f32 v[168:169], v[168:169], v[74:75]
	v_cvt_pk_bf16_f32 v164, v164, v165
	v_cvt_pk_bf16_f32 v165, v168, v169
	v_mul_f32_e32 v168, 0xbfb8aa3b, v0
	v_mul_f32_e32 v169, 0xbfb8aa3b, v1
	v_exp_f32_e32 v168, v168
	v_exp_f32_e32 v169, v169
	v_mad_u64_u32 v[166:167], s[18:19], s78, v160, 0
	v_pk_mul_f32 v[170:171], v[12:13], v[170:171]
	v_pk_mul_f32 v[172:173], v[14:15], v[172:173]
	v_add3_u32 v167, v167, v157, v161
	v_pk_mul_f32 v[170:171], v[170:171], v[76:77]
	v_pk_mul_f32 v[172:173], v[172:173], v[78:79]
	v_lshl_add_u64 v[174:175], v[166:167], 1, v[140:141]
	v_cvt_pk_bf16_f32 v166, v170, v171
	v_cvt_pk_bf16_f32 v167, v172, v173
	global_store_dwordx4 v[174:175], v[164:167], off
	v_mul_f32_e32 v170, 0xbfb8aa3b, v4
	v_mul_f32_e32 v171, 0xbfb8aa3b, v5
	v_add_f32_e32 v164, 1.0, v168
	v_add_f32_e32 v165, 1.0, v169
	v_mul_f32_e32 v168, 0xbfb8aa3b, v2
	v_mul_f32_e32 v169, 0xbfb8aa3b, v3
	v_mul_f32_e32 v172, 0xbfb8aa3b, v6
	v_mul_f32_e32 v173, 0xbfb8aa3b, v7
	v_exp_f32_e32 v168, v168
	v_exp_f32_e32 v169, v169
	v_exp_f32_e32 v170, v170
	v_exp_f32_e32 v171, v171
	v_exp_f32_e32 v172, v172
	v_exp_f32_e32 v173, v173
	v_add_f32_e32 v168, 1.0, v168
	v_add_f32_e32 v169, 1.0, v169
	v_add_f32_e32 v170, 1.0, v170
	v_add_f32_e32 v171, 1.0, v171
	v_add_f32_e32 v172, 1.0, v172
	v_add_f32_e32 v173, 1.0, v173
	v_rcp_f32_e32 v164, v164
	v_rcp_f32_e32 v165, v165
	v_rcp_f32_e32 v168, v168
	v_rcp_f32_e32 v169, v169
	v_rcp_f32_e32 v170, v170
	v_rcp_f32_e32 v171, v171
	v_rcp_f32_e32 v172, v172
	v_rcp_f32_e32 v173, v173
	v_mad_u64_u32 v[166:167], s[18:19], s78, v158, 0
	v_pk_mul_f32 v[164:165], v[0:1], v[164:165]
	v_pk_mul_f32 v[168:169], v[2:3], v[168:169]
	v_pk_mul_f32 v[170:171], v[4:5], v[170:171]
	v_pk_mul_f32 v[172:173], v[6:7], v[172:173]
	v_add3_u32 v167, v167, v157, v159
	v_pk_mul_f32 v[164:165], v[164:165], v[56:57]
	v_pk_mul_f32 v[168:169], v[168:169], v[58:59]
	v_pk_mul_f32 v[170:171], v[170:171], v[64:65]
	v_pk_mul_f32 v[172:173], v[172:173], v[66:67]
	v_lshl_add_u64 v[174:175], v[166:167], 1, v[140:141]
	v_cvt_pk_bf16_f32 v164, v164, v165
	v_cvt_pk_bf16_f32 v165, v168, v169
	v_cvt_pk_bf16_f32 v166, v170, v171
	v_cvt_pk_bf16_f32 v167, v172, v173
	global_store_dwordx4 v[174:175], v[164:167], off
	v_mul_lo_u32 v168, s78, v156
	v_mul_f32_e32 v169, 0xbfb8aa3b, v63
	v_mad_u64_u32 v[166:167], s[18:19], s78, v154, 0
	v_mul_f32_e32 v164, 0xbfb8aa3b, v60
	v_mul_f32_e32 v165, 0xbfb8aa3b, v61
	v_add3_u32 v167, v167, v168, v155
	v_mul_f32_e32 v168, 0xbfb8aa3b, v62
	v_mul_f32_e32 v170, 0xbfb8aa3b, v68
	v_mul_f32_e32 v171, 0xbfb8aa3b, v69
	v_mul_f32_e32 v172, 0xbfb8aa3b, v70
	v_mul_f32_e32 v173, 0xbfb8aa3b, v71
	v_exp_f32_e32 v164, v164
	v_exp_f32_e32 v165, v165
	v_exp_f32_e32 v168, v168
	v_exp_f32_e32 v169, v169
	v_exp_f32_e32 v170, v170
	v_exp_f32_e32 v171, v171
	v_exp_f32_e32 v172, v172
	v_exp_f32_e32 v173, v173
	v_add_f32_e32 v164, 1.0, v164
	v_add_f32_e32 v165, 1.0, v165
	v_add_f32_e32 v168, 1.0, v168
	v_add_f32_e32 v169, 1.0, v169
	v_add_f32_e32 v170, 1.0, v170
	v_add_f32_e32 v171, 1.0, v171
; DI unsigned pk2(float lo, float hi) { f32x2 v = {lo, hi}; bf16v2 b = __builtin_convertvector(v, bf16v2); return __builtin_bit_cast(unsigned, b); }
; DI float silu_f(float x) { return x * __builtin_amdgcn_rcpf(1.f + __expf(-x)); }
;     DI void operator()(const f32x4 (&acc)[2][2][4][2], const Unit& u, int wr, int wc, int fr, int fq) const {
;         const int row0 = u.pm * BM + wr * 64 + fr, col0 = u.pn * HALF + wc * 32 + 8 * fq;
; #pragma unroll
;         for (int ai = 0; ai < 2; ++ai)
; #pragma unroll
;             for (int m = 0; m < 4; ++m) { bf16_t* rowp = O + (size_t)(row0 + ai * HALF + m * 16) * ldc + col0;
;                 float r[8];
; #pragma unroll
;                 for (int n = 0; n < 2; ++n)
; #pragma unroll
;                     for (int e = 0; e < 4; ++e) { const float g = acc[ai][0][m][n][e], up = acc[ai][1][m][n][e]; r[n * 4 + e] = silu_f(g) * up; }
;                 u32x4 o; o.x = pk2(r[0], r[1]); o.y = pk2(r[2], r[3]); o.z = pk2(r[4], r[5]); o.w = pk2(r[6], r[7]);
;                 *(u32x4*)rowp = o; }
; template <class Epi>
; DI void gemm_phase(LAS unsigned char* lds, const Gemm g, const StaticOrder& S, const Epi& E, const int tid) {
;     ...
;         E(acc, cur, wr, wc, fr, fq);
;         if (!has_next) break;
	v_add_f32_e32 v172, 1.0, v172
	v_add_f32_e32 v173, 1.0, v173
	v_rcp_f32_e32 v164, v164
	v_rcp_f32_e32 v165, v165
	v_rcp_f32_e32 v168, v168
	v_rcp_f32_e32 v169, v169
	v_rcp_f32_e32 v170, v170
	v_rcp_f32_e32 v171, v171
	v_rcp_f32_e32 v172, v172
	v_rcp_f32_e32 v173, v173
	v_pk_mul_f32 v[164:165], v[60:61], v[164:165]
	v_pk_mul_f32 v[168:169], v[62:63], v[168:169]
	v_pk_mul_f32 v[170:171], v[68:69], v[170:171]
	v_pk_mul_f32 v[172:173], v[70:71], v[172:173]
	v_pk_mul_f32 v[164:165], v[164:165], v[120:121]
	v_pk_mul_f32 v[168:169], v[168:169], v[122:123]
	v_pk_mul_f32 v[170:171], v[170:171], v[124:125]
	v_pk_mul_f32 v[172:173], v[172:173], v[126:127]
	v_lshl_add_u64 v[174:175], v[166:167], 1, v[140:141]
	v_cvt_pk_bf16_f32 v164, v164, v165
	v_cvt_pk_bf16_f32 v165, v168, v169
	v_cvt_pk_bf16_f32 v166, v170, v171
	v_cvt_pk_bf16_f32 v167, v172, v173
	global_store_dwordx4 v[174:175], v[164:167], off
	v_mul_lo_u32 v168, s78, v153
	v_mul_f32_e32 v169, 0xbfb8aa3b, v51
	v_mad_u64_u32 v[166:167], s[18:19], s78, v151, 0
	v_mul_f32_e32 v164, 0xbfb8aa3b, v48
	v_mul_f32_e32 v165, 0xbfb8aa3b, v49
	v_add3_u32 v167, v167, v168, v152
	v_mul_f32_e32 v168, 0xbfb8aa3b, v50
	v_mul_f32_e32 v170, 0xbfb8aa3b, v52
	v_mul_f32_e32 v171, 0xbfb8aa3b, v53
	v_mul_f32_e32 v172, 0xbfb8aa3b, v54
	v_mul_f32_e32 v173, 0xbfb8aa3b, v55
	v_exp_f32_e32 v164, v164
	v_exp_f32_e32 v165, v165
	v_exp_f32_e32 v168, v168
	v_exp_f32_e32 v169, v169
	v_exp_f32_e32 v170, v170
	v_exp_f32_e32 v171, v171
	v_exp_f32_e32 v172, v172
	v_exp_f32_e32 v173, v173
	v_add_f32_e32 v164, 1.0, v164
	v_add_f32_e32 v165, 1.0, v165
	v_add_f32_e32 v168, 1.0, v168
	v_add_f32_e32 v169, 1.0, v169
	v_add_f32_e32 v170, 1.0, v170
	v_add_f32_e32 v171, 1.0, v171
	v_add_f32_e32 v172, 1.0, v172
	v_add_f32_e32 v173, 1.0, v173
	v_rcp_f32_e32 v164, v164
	v_rcp_f32_e32 v165, v165
	v_rcp_f32_e32 v168, v168
	v_rcp_f32_e32 v169, v169
	v_rcp_f32_e32 v170, v170
	v_rcp_f32_e32 v171, v171
	v_rcp_f32_e32 v172, v172
	v_rcp_f32_e32 v173, v173
	v_pk_mul_f32 v[164:165], v[48:49], v[164:165]
	v_pk_mul_f32 v[168:169], v[50:51], v[168:169]
	v_pk_mul_f32 v[170:171], v[52:53], v[170:171]
	v_pk_mul_f32 v[172:173], v[54:55], v[172:173]
	v_pk_mul_f32 v[164:165], v[164:165], v[112:113]
	v_pk_mul_f32 v[168:169], v[168:169], v[114:115]
	v_pk_mul_f32 v[170:171], v[170:171], v[116:117]
	v_pk_mul_f32 v[172:173], v[172:173], v[118:119]
	v_lshl_add_u64 v[174:175], v[166:167], 1, v[140:141]
	v_cvt_pk_bf16_f32 v164, v164, v165
	v_cvt_pk_bf16_f32 v165, v168, v169
	v_cvt_pk_bf16_f32 v166, v170, v171
	v_cvt_pk_bf16_f32 v167, v172, v173
	global_store_dwordx4 v[174:175], v[164:167], off
	v_mul_lo_u32 v169, s79, v150
	v_mul_f32_e32 v170, 0xbfb8aa3b, v44
	v_ashrrev_i32_e32 v164, 31, v150
	v_mul_lo_u32 v168, s78, v164
	v_mad_u64_u32 v[166:167], s[18:19], s78, v150, 0
	v_mul_f32_e32 v164, 0xbfb8aa3b, v40
	v_mul_f32_e32 v165, 0xbfb8aa3b, v41
	v_add3_u32 v167, v167, v168, v169
	v_mul_f32_e32 v168, 0xbfb8aa3b, v42
	v_mul_f32_e32 v169, 0xbfb8aa3b, v43
	v_mul_f32_e32 v171, 0xbfb8aa3b, v45
	v_mul_f32_e32 v172, 0xbfb8aa3b, v46
	v_mul_f32_e32 v173, 0xbfb8aa3b, v47
	v_exp_f32_e32 v164, v164
	v_exp_f32_e32 v165, v165
	v_exp_f32_e32 v168, v168
	v_exp_f32_e32 v169, v169
	v_exp_f32_e32 v170, v170
	v_exp_f32_e32 v171, v171
	v_exp_f32_e32 v172, v172
	v_exp_f32_e32 v173, v173
	v_add_f32_e32 v164, 1.0, v164
	v_add_f32_e32 v165, 1.0, v165
	v_add_f32_e32 v168, 1.0, v168
	v_add_f32_e32 v169, 1.0, v169
	v_add_f32_e32 v170, 1.0, v170
	v_add_f32_e32 v171, 1.0, v171
	v_add_f32_e32 v172, 1.0, v172
	v_add_f32_e32 v173, 1.0, v173
	v_rcp_f32_e32 v164, v164
	v_rcp_f32_e32 v165, v165
	v_rcp_f32_e32 v168, v168
	v_rcp_f32_e32 v169, v169
	v_rcp_f32_e32 v170, v170
	v_rcp_f32_e32 v171, v171
	v_rcp_f32_e32 v172, v172
	v_rcp_f32_e32 v173, v173
	v_pk_mul_f32 v[164:165], v[40:41], v[164:165]
	v_pk_mul_f32 v[168:169], v[42:43], v[168:169]
	v_pk_mul_f32 v[170:171], v[44:45], v[170:171]
	v_pk_mul_f32 v[172:173], v[46:47], v[172:173]
	v_pk_mul_f32 v[164:165], v[164:165], v[104:105]
	v_pk_mul_f32 v[168:169], v[168:169], v[106:107]
	v_pk_mul_f32 v[170:171], v[170:171], v[108:109]
	v_pk_mul_f32 v[172:173], v[172:173], v[110:111]
	v_lshl_add_u64 v[174:175], v[166:167], 1, v[140:141]
	v_cvt_pk_bf16_f32 v164, v164, v165
	v_cvt_pk_bf16_f32 v165, v168, v169
	v_cvt_pk_bf16_f32 v166, v170, v171
	v_cvt_pk_bf16_f32 v167, v172, v173
	global_store_dwordx4 v[174:175], v[164:167], off
	v_mul_lo_u32 v169, s79, v149
	v_mul_f32_e32 v170, 0xbfb8aa3b, v36
	v_ashrrev_i32_e32 v164, 31, v149
	v_mul_lo_u32 v168, s78, v164
	v_mad_u64_u32 v[166:167], s[18:19], s78, v149, 0
	v_mul_f32_e32 v164, 0xbfb8aa3b, v32
	v_mul_f32_e32 v165, 0xbfb8aa3b, v33
	v_add3_u32 v167, v167, v168, v169
	v_mul_f32_e32 v168, 0xbfb8aa3b, v34
	v_mul_f32_e32 v169, 0xbfb8aa3b, v35
	v_mul_f32_e32 v171, 0xbfb8aa3b, v37
	v_mul_f32_e32 v172, 0xbfb8aa3b, v38
	v_mul_f32_e32 v173, 0xbfb8aa3b, v39
	v_exp_f32_e32 v164, v164
	v_exp_f32_e32 v165, v165
	v_exp_f32_e32 v168, v168
	v_exp_f32_e32 v169, v169
	v_exp_f32_e32 v170, v170
	v_exp_f32_e32 v171, v171
	v_exp_f32_e32 v172, v172
	v_exp_f32_e32 v173, v173
	v_add_f32_e32 v164, 1.0, v164
	v_add_f32_e32 v165, 1.0, v165
	v_add_f32_e32 v168, 1.0, v168
	v_add_f32_e32 v169, 1.0, v169
	v_add_f32_e32 v170, 1.0, v170
	v_add_f32_e32 v171, 1.0, v171
	v_add_f32_e32 v172, 1.0, v172
	v_add_f32_e32 v173, 1.0, v173
	v_rcp_f32_e32 v164, v164
	v_rcp_f32_e32 v165, v165
	v_rcp_f32_e32 v168, v168
	v_rcp_f32_e32 v169, v169
	v_rcp_f32_e32 v170, v170
	v_rcp_f32_e32 v171, v171
	v_rcp_f32_e32 v172, v172
	v_rcp_f32_e32 v173, v173
	v_pk_mul_f32 v[164:165], v[32:33], v[164:165]
	v_pk_mul_f32 v[168:169], v[34:35], v[168:169]
	v_pk_mul_f32 v[170:171], v[36:37], v[170:171]
	v_pk_mul_f32 v[172:173], v[38:39], v[172:173]
	v_pk_mul_f32 v[164:165], v[164:165], v[92:93]
	v_pk_mul_f32 v[168:169], v[168:169], v[94:95]
	v_pk_mul_f32 v[170:171], v[170:171], v[100:101]
	v_pk_mul_f32 v[172:173], v[172:173], v[102:103]
	v_lshl_add_u64 v[140:141], v[166:167], 1, v[140:141]
	v_cvt_pk_bf16_f32 v164, v164, v165
	v_cvt_pk_bf16_f32 v165, v168, v169
	v_cvt_pk_bf16_f32 v166, v170, v171
	v_cvt_pk_bf16_f32 v167, v172, v173
	global_store_dwordx4 v[140:141], v[164:167], off
	s_cbranch_execnz .LBB0_748
	s_branch .LBB0_747
